# P1 RoPE tiles fetch their cos/sin table share in the tile header (no memory drain in the epilogue)
# baseline (speedup 1.0000x reference)
.LBB0_182:
	s_mul_hi_u32 s0, s34, 0xaaaaaaab
	s_lshr_b32 s12, s0, 2
	s_mul_i32 s0, s12, 6
	s_sub_i32 s0, s34, s0
	v_readlane_b32 s10, v246, 6
	s_add_i32 s13, s0, s10
	s_cmp_lt_u32 s13, 16
	s_cbranch_scc1 .Lp1h_norope
	s_cmp_lt_u32 s12, 5
	s_cbranch_scc0 .Lp1h_norope
	v_readlane_b32 s10, v247, 53
	v_readlane_b32 s11, v247, 54
	v_lshlrev_b32_e32 v2, 5, v187
	s_nop 4
	global_load_dwordx4 v[222:225], v2, s[10:11]
	global_load_dwordx4 v[226:229], v2, s[10:11] offset:16

.Lp1e_rope:
	s_nop 7
	s_nop 7
	s_barrier
	v_lshlrev_b32_e32 v174, 5, v187
	s_mul_i32 s0, s13, 0x140000
	s_add_u32 s10, s18, s0
	s_addc_u32 s11, s19, 0
	s_lshl_b32 s0, s12, 8
	s_add_u32 s10, s10, s0
	s_addc_u32 s11, s11, 0
	v_lshl_add_u32 v206, v209, 2, v219
	v_mul_u32_u24_e32 v206, 0x1400, v206
	v_lshl_add_u32 v206, v208, 1, v206
	s_lshl_b32 s0, s13, 2
	v_lshrrev_b32_e32 v178, 6, v219
	v_add_u32_e32 v178, s0, v178
	v_and_b32_e32 v178, 31, v178
	v_lshl_add_u32 v178, v178, 6, v220
	v_lshl_add_u32 v179, v209, 8, v220
	v_cndmask_b32_e64 v178, v179, v178, s[36:37]
	v_cndmask_b32_e64 v179, 64, 0, s[36:37]
	v_mul_u32_u24_e32 v207, 5, v179
	ds_write_b128 v174, v[222:225] offset:57344
	ds_write_b128 v174, v[226:229] offset:57360
	s_waitcnt lgkmcnt(0)
	s_barrier
	ds_read_b128 v[238:241], v178 offset:57344
	ds_read_b128 v[170:173], v178 offset:61440
	v_add_u32_e32 v178, v178, v179
	ds_read_b128 v[174:177], v178 offset:57344
	ds_read_b128 v[190:193], v178 offset:61440
	v_add_u32_e32 v178, v178, v179
	ds_read_b128 v[248:251], v178 offset:57344
	ds_read_b128 v[252:255], v178 offset:61440
	v_add_u32_e32 v178, v178, v179
	s_waitcnt lgkmcnt(4)
	v_mul_f32_dpp v200, -v114, v170 row_shl:4 row_mask:0xf bank_mask:0x5
	v_mul_f32_dpp v200, v114, v170 row_shr:4 row_mask:0xf bank_mask:0xa
	v_mul_f32_dpp v201, -v82, v171 row_shl:4 row_mask:0xf bank_mask:0x5
	v_mul_f32_dpp v201, v82, v171 row_shr:4 row_mask:0xf bank_mask:0xa
	v_mul_f32_dpp v202, -v98, v172 row_shl:4 row_mask:0xf bank_mask:0x5
	v_mul_f32_dpp v202, v98, v172 row_shr:4 row_mask:0xf bank_mask:0xa
	v_mul_f32_dpp v203, -v66, v173 row_shl:4 row_mask:0xf bank_mask:0x5
	v_mul_f32_dpp v203, v66, v173 row_shr:4 row_mask:0xf bank_mask:0xa
	v_fma_f32 v114, v114, v238, v200
	v_fma_f32 v82, v82, v239, v201
	v_fma_f32 v98, v98, v240, v202
	v_fma_f32 v66, v66, v241, v203
	v_cvt_pk_bf16_f32 v180, v114, v82
	v_cvt_pk_bf16_f32 v181, v98, v66
	global_store_dwordx2 v206, v[180:181], s[10:11]
	s_add_u32 s10, s10, 0x1400
	s_addc_u32 s11, s11, 0
	ds_read_b128 v[238:241], v178 offset:57344
	ds_read_b128 v[170:173], v178 offset:61440
	v_add_u32_e32 v178, v178, v207
	s_waitcnt lgkmcnt(4)
	v_mul_f32_dpp v200, -v115, v190 row_shl:4 row_mask:0xf bank_mask:0x5
	v_mul_f32_dpp v200, v115, v190 row_shr:4 row_mask:0xf bank_mask:0xa
	v_mul_f32_dpp v201, -v83, v191 row_shl:4 row_mask:0xf bank_mask:0x5
	v_mul_f32_dpp v201, v83, v191 row_shr:4 row_mask:0xf bank_mask:0xa
	v_mul_f32_dpp v202, -v99, v192 row_shl:4 row_mask:0xf bank_mask:0x5
	v_mul_f32_dpp v202, v99, v192 row_shr:4 row_mask:0xf bank_mask:0xa
	v_mul_f32_dpp v203, -v67, v193 row_shl:4 row_mask:0xf bank_mask:0x5
	v_mul_f32_dpp v203, v67, v193 row_shr:4 row_mask:0xf bank_mask:0xa
	v_fma_f32 v115, v115, v174, v200
	v_fma_f32 v83, v83, v175, v201
	v_fma_f32 v99, v99, v176, v202
	v_fma_f32 v67, v67, v177, v203
	v_cvt_pk_bf16_f32 v204, v115, v83
	v_cvt_pk_bf16_f32 v205, v99, v67
	global_store_dwordx2 v206, v[204:205], s[10:11]
	s_add_u32 s10, s10, 0x1400
	s_addc_u32 s11, s11, 0
	ds_read_b128 v[174:177], v178 offset:57344
	ds_read_b128 v[190:193], v178 offset:61440
	v_add_u32_e32 v178, v178, v179
	s_waitcnt lgkmcnt(4)
	v_mul_f32_dpp v200, -v116, v252 row_shl:4 row_mask:0xf bank_mask:0x5
	v_mul_f32_dpp v200, v116, v252 row_shr:4 row_mask:0xf bank_mask:0xa
	v_mul_f32_dpp v201, -v84, v253 row_shl:4 row_mask:0xf bank_mask:0x5
	v_mul_f32_dpp v201, v84, v253 row_shr:4 row_mask:0xf bank_mask:0xa
	v_mul_f32_dpp v202, -v100, v254 row_shl:4 row_mask:0xf bank_mask:0x5
	v_mul_f32_dpp v202, v100, v254 row_shr:4 row_mask:0xf bank_mask:0xa
	v_mul_f32_dpp v203, -v68, v255 row_shl:4 row_mask:0xf bank_mask:0x5
	v_mul_f32_dpp v203, v68, v255 row_shr:4 row_mask:0xf bank_mask:0xa
	v_fma_f32 v116, v116, v248, v200
	v_fma_f32 v84, v84, v249, v201
	v_fma_f32 v100, v100, v250, v202
	v_fma_f32 v68, v68, v251, v203
	v_cvt_pk_bf16_f32 v180, v116, v84
	v_cvt_pk_bf16_f32 v181, v100, v68
	global_store_dwordx2 v206, v[180:181], s[10:11]
	s_add_u32 s10, s10, 0x1400
	s_addc_u32 s11, s11, 0
	ds_read_b128 v[248:251], v178 offset:57344
	ds_read_b128 v[252:255], v178 offset:61440
	v_add_u32_e32 v178, v178, v179
	s_waitcnt lgkmcnt(4)
	v_mul_f32_dpp v200, -v117, v170 row_shl:4 row_mask:0xf bank_mask:0x5
	v_mul_f32_dpp v200, v117, v170 row_shr:4 row_mask:0xf bank_mask:0xa
	v_mul_f32_dpp v201, -v85, v171 row_shl:4 row_mask:0xf bank_mask:0x5
	v_mul_f32_dpp v201, v85, v171 row_shr:4 row_mask:0xf bank_mask:0xa
	v_mul_f32_dpp v202, -v101, v172 row_shl:4 row_mask:0xf bank_mask:0x5
	v_mul_f32_dpp v202, v101, v172 row_shr:4 row_mask:0xf bank_mask:0xa
	v_mul_f32_dpp v203, -v69, v173 row_shl:4 row_mask:0xf bank_mask:0x5
	v_mul_f32_dpp v203, v69, v173 row_shr:4 row_mask:0xf bank_mask:0xa
	v_fma_f32 v117, v117, v238, v200
	v_fma_f32 v85, v85, v239, v201
	v_fma_f32 v101, v101, v240, v202
	v_fma_f32 v69, v69, v241, v203
	v_cvt_pk_bf16_f32 v204, v117, v85
	v_cvt_pk_bf16_f32 v205, v101, v69
	global_store_dwordx2 v206, v[204:205], s[10:11]
	s_add_u32 s10, s10, 0x6400
	s_addc_u32 s11, s11, 0
	ds_read_b128 v[238:241], v178 offset:57344
	ds_read_b128 v[170:173], v178 offset:61440
	v_add_u32_e32 v178, v178, v179
	s_waitcnt lgkmcnt(4)
	v_mul_f32_dpp v200, -v118, v190 row_shl:4 row_mask:0xf bank_mask:0x5
	v_mul_f32_dpp v200, v118, v190 row_shr:4 row_mask:0xf bank_mask:0xa
	v_mul_f32_dpp v201, -v86, v191 row_shl:4 row_mask:0xf bank_mask:0x5
	v_mul_f32_dpp v201, v86, v191 row_shr:4 row_mask:0xf bank_mask:0xa
	v_mul_f32_dpp v202, -v102, v192 row_shl:4 row_mask:0xf bank_mask:0x5
	v_mul_f32_dpp v202, v102, v192 row_shr:4 row_mask:0xf bank_mask:0xa
	v_mul_f32_dpp v203, -v70, v193 row_shl:4 row_mask:0xf bank_mask:0x5
	v_mul_f32_dpp v203, v70, v193 row_shr:4 row_mask:0xf bank_mask:0xa
	v_fma_f32 v118, v118, v174, v200
	v_fma_f32 v86, v86, v175, v201
	v_fma_f32 v102, v102, v176, v202
	v_fma_f32 v70, v70, v177, v203
	v_cvt_pk_bf16_f32 v180, v118, v86
	v_cvt_pk_bf16_f32 v181, v102, v70
	global_store_dwordx2 v206, v[180:181], s[10:11]
	s_add_u32 s10, s10, 0x1400
	s_addc_u32 s11, s11, 0
	ds_read_b128 v[174:177], v178 offset:57344
	ds_read_b128 v[190:193], v178 offset:61440
	v_add_u32_e32 v178, v178, v207
	s_waitcnt lgkmcnt(4)
	v_mul_f32_dpp v200, -v119, v252 row_shl:4 row_mask:0xf bank_mask:0x5
	v_mul_f32_dpp v200, v119, v252 row_shr:4 row_mask:0xf bank_mask:0xa
	v_mul_f32_dpp v201, -v87, v253 row_shl:4 row_mask:0xf bank_mask:0x5
	v_mul_f32_dpp v201, v87, v253 row_shr:4 row_mask:0xf bank_mask:0xa
	v_mul_f32_dpp v202, -v103, v254 row_shl:4 row_mask:0xf bank_mask:0x5
	v_mul_f32_dpp v202, v103, v254 row_shr:4 row_mask:0xf bank_mask:0xa
	v_mul_f32_dpp v203, -v71, v255 row_shl:4 row_mask:0xf bank_mask:0x5
	v_mul_f32_dpp v203, v71, v255 row_shr:4 row_mask:0xf bank_mask:0xa
	v_fma_f32 v119, v119, v248, v200
	v_fma_f32 v87, v87, v249, v201
	v_fma_f32 v103, v103, v250, v202
	v_fma_f32 v71, v71, v251, v203
	v_cvt_pk_bf16_f32 v204, v119, v87
	v_cvt_pk_bf16_f32 v205, v103, v71
	global_store_dwordx2 v206, v[204:205], s[10:11]
	s_add_u32 s10, s10, 0x1400
	s_addc_u32 s11, s11, 0
	ds_read_b128 v[248:251], v178 offset:57344
	ds_read_b128 v[252:255], v178 offset:61440
	v_add_u32_e32 v178, v178, v179
	s_waitcnt lgkmcnt(4)
	v_mul_f32_dpp v200, -v120, v170 row_shl:4 row_mask:0xf bank_mask:0x5
	v_mul_f32_dpp v200, v120, v170 row_shr:4 row_mask:0xf bank_mask:0xa
	v_mul_f32_dpp v201, -v88, v171 row_shl:4 row_mask:0xf bank_mask:0x5
	v_mul_f32_dpp v201, v88, v171 row_shr:4 row_mask:0xf bank_mask:0xa
	v_mul_f32_dpp v202, -v104, v172 row_shl:4 row_mask:0xf bank_mask:0x5
	v_mul_f32_dpp v202, v104, v172 row_shr:4 row_mask:0xf bank_mask:0xa
	v_mul_f32_dpp v203, -v72, v173 row_shl:4 row_mask:0xf bank_mask:0x5
	v_mul_f32_dpp v203, v72, v173 row_shr:4 row_mask:0xf bank_mask:0xa
	v_fma_f32 v120, v120, v238, v200
	v_fma_f32 v88, v88, v239, v201
	v_fma_f32 v104, v104, v240, v202
	v_fma_f32 v72, v72, v241, v203
	v_cvt_pk_bf16_f32 v180, v120, v88
	v_cvt_pk_bf16_f32 v181, v104, v72
	global_store_dwordx2 v206, v[180:181], s[10:11]
	s_add_u32 s10, s10, 0x1400
	s_addc_u32 s11, s11, 0
	ds_read_b128 v[238:241], v178 offset:57344
	ds_read_b128 v[170:173], v178 offset:61440
	v_add_u32_e32 v178, v178, v179
	s_waitcnt lgkmcnt(4)
	v_mul_f32_dpp v200, -v121, v190 row_shl:4 row_mask:0xf bank_mask:0x5
	v_mul_f32_dpp v200, v121, v190 row_shr:4 row_mask:0xf bank_mask:0xa
	v_mul_f32_dpp v201, -v89, v191 row_shl:4 row_mask:0xf bank_mask:0x5
	v_mul_f32_dpp v201, v89, v191 row_shr:4 row_mask:0xf bank_mask:0xa
	v_mul_f32_dpp v202, -v105, v192 row_shl:4 row_mask:0xf bank_mask:0x5
	v_mul_f32_dpp v202, v105, v192 row_shr:4 row_mask:0xf bank_mask:0xa
	v_mul_f32_dpp v203, -v73, v193 row_shl:4 row_mask:0xf bank_mask:0x5
	v_mul_f32_dpp v203, v73, v193 row_shr:4 row_mask:0xf bank_mask:0xa
	v_fma_f32 v121, v121, v174, v200
	v_fma_f32 v89, v89, v175, v201
	v_fma_f32 v105, v105, v176, v202
	v_fma_f32 v73, v73, v177, v203
	v_cvt_pk_bf16_f32 v204, v121, v89
	v_cvt_pk_bf16_f32 v205, v105, v73
	global_store_dwordx2 v206, v[204:205], s[10:11]
	s_add_u32 s10, s10, 0x6400
	s_addc_u32 s11, s11, 0
	ds_read_b128 v[174:177], v178 offset:57344
	ds_read_b128 v[190:193], v178 offset:61440
	v_add_u32_e32 v178, v178, v179
	s_waitcnt lgkmcnt(4)
	v_mul_f32_dpp v200, -v122, v252 row_shl:4 row_mask:0xf bank_mask:0x5
	v_mul_f32_dpp v200, v122, v252 row_shr:4 row_mask:0xf bank_mask:0xa
	v_mul_f32_dpp v201, -v90, v253 row_shl:4 row_mask:0xf bank_mask:0x5
	v_mul_f32_dpp v201, v90, v253 row_shr:4 row_mask:0xf bank_mask:0xa
	v_mul_f32_dpp v202, -v106, v254 row_shl:4 row_mask:0xf bank_mask:0x5
	v_mul_f32_dpp v202, v106, v254 row_shr:4 row_mask:0xf bank_mask:0xa
	v_mul_f32_dpp v203, -v74, v255 row_shl:4 row_mask:0xf bank_mask:0x5
	v_mul_f32_dpp v203, v74, v255 row_shr:4 row_mask:0xf bank_mask:0xa
	v_fma_f32 v122, v122, v248, v200
	v_fma_f32 v90, v90, v249, v201
	v_fma_f32 v106, v106, v250, v202
	v_fma_f32 v74, v74, v251, v203
	v_cvt_pk_bf16_f32 v180, v122, v90
	v_cvt_pk_bf16_f32 v181, v106, v74
	global_store_dwordx2 v206, v[180:181], s[10:11]
	s_add_u32 s10, s10, 0x1400
	s_addc_u32 s11, s11, 0
	ds_read_b128 v[248:251], v178 offset:57344
	ds_read_b128 v[252:255], v178 offset:61440
	v_add_u32_e32 v178, v178, v207
	s_waitcnt lgkmcnt(4)
	v_mul_f32_dpp v200, -v123, v170 row_shl:4 row_mask:0xf bank_mask:0x5
	v_mul_f32_dpp v200, v123, v170 row_shr:4 row_mask:0xf bank_mask:0xa
	v_mul_f32_dpp v201, -v91, v171 row_shl:4 row_mask:0xf bank_mask:0x5
	v_mul_f32_dpp v201, v91, v171 row_shr:4 row_mask:0xf bank_mask:0xa
	v_mul_f32_dpp v202, -v107, v172 row_shl:4 row_mask:0xf bank_mask:0x5
	v_mul_f32_dpp v202, v107, v172 row_shr:4 row_mask:0xf bank_mask:0xa
	v_mul_f32_dpp v203, -v75, v173 row_shl:4 row_mask:0xf bank_mask:0x5
	v_mul_f32_dpp v203, v75, v173 row_shr:4 row_mask:0xf bank_mask:0xa
	v_fma_f32 v123, v123, v238, v200
	v_fma_f32 v91, v91, v239, v201
	v_fma_f32 v107, v107, v240, v202
	v_fma_f32 v75, v75, v241, v203
	v_cvt_pk_bf16_f32 v204, v123, v91
	v_cvt_pk_bf16_f32 v205, v107, v75
	global_store_dwordx2 v206, v[204:205], s[10:11]
	s_add_u32 s10, s10, 0x1400
	s_addc_u32 s11, s11, 0
	ds_read_b128 v[238:241], v178 offset:57344
	ds_read_b128 v[170:173], v178 offset:61440
	v_add_u32_e32 v178, v178, v179
	s_waitcnt lgkmcnt(4)
	v_mul_f32_dpp v200, -v124, v190 row_shl:4 row_mask:0xf bank_mask:0x5
	v_mul_f32_dpp v200, v124, v190 row_shr:4 row_mask:0xf bank_mask:0xa
	v_mul_f32_dpp v201, -v92, v191 row_shl:4 row_mask:0xf bank_mask:0x5
	v_mul_f32_dpp v201, v92, v191 row_shr:4 row_mask:0xf bank_mask:0xa
	v_mul_f32_dpp v202, -v108, v192 row_shl:4 row_mask:0xf bank_mask:0x5
	v_mul_f32_dpp v202, v108, v192 row_shr:4 row_mask:0xf bank_mask:0xa
	v_mul_f32_dpp v203, -v76, v193 row_shl:4 row_mask:0xf bank_mask:0x5
	v_mul_f32_dpp v203, v76, v193 row_shr:4 row_mask:0xf bank_mask:0xa
	v_fma_f32 v124, v124, v174, v200
	v_fma_f32 v92, v92, v175, v201
	v_fma_f32 v108, v108, v176, v202
	v_fma_f32 v76, v76, v177, v203
	v_cvt_pk_bf16_f32 v180, v124, v92
	v_cvt_pk_bf16_f32 v181, v108, v76
	global_store_dwordx2 v206, v[180:181], s[10:11]
	s_add_u32 s10, s10, 0x1400
	s_addc_u32 s11, s11, 0
	ds_read_b128 v[174:177], v178 offset:57344
	ds_read_b128 v[190:193], v178 offset:61440
	v_add_u32_e32 v178, v178, v179
	s_waitcnt lgkmcnt(4)
	v_mul_f32_dpp v200, -v125, v252 row_shl:4 row_mask:0xf bank_mask:0x5
	v_mul_f32_dpp v200, v125, v252 row_shr:4 row_mask:0xf bank_mask:0xa
	v_mul_f32_dpp v201, -v93, v253 row_shl:4 row_mask:0xf bank_mask:0x5
	v_mul_f32_dpp v201, v93, v253 row_shr:4 row_mask:0xf bank_mask:0xa
	v_mul_f32_dpp v202, -v109, v254 row_shl:4 row_mask:0xf bank_mask:0x5
	v_mul_f32_dpp v202, v109, v254 row_shr:4 row_mask:0xf bank_mask:0xa
	v_mul_f32_dpp v203, -v77, v255 row_shl:4 row_mask:0xf bank_mask:0x5
	v_mul_f32_dpp v203, v77, v255 row_shr:4 row_mask:0xf bank_mask:0xa
	v_fma_f32 v125, v125, v248, v200
	v_fma_f32 v93, v93, v249, v201
	v_fma_f32 v109, v109, v250, v202
	v_fma_f32 v77, v77, v251, v203
	v_cvt_pk_bf16_f32 v204, v125, v93
	v_cvt_pk_bf16_f32 v205, v109, v77
	global_store_dwordx2 v206, v[204:205], s[10:11]
	s_add_u32 s10, s10, 0x6400
	s_addc_u32 s11, s11, 0
	ds_read_b128 v[248:251], v178 offset:57344
	ds_read_b128 v[252:255], v178 offset:61440
	v_add_u32_e32 v178, v178, v179
	s_waitcnt lgkmcnt(4)
	v_mul_f32_dpp v200, -v126, v170 row_shl:4 row_mask:0xf bank_mask:0x5
	v_mul_f32_dpp v200, v126, v170 row_shr:4 row_mask:0xf bank_mask:0xa
	v_mul_f32_dpp v201, -v94, v171 row_shl:4 row_mask:0xf bank_mask:0x5
	v_mul_f32_dpp v201, v94, v171 row_shr:4 row_mask:0xf bank_mask:0xa
	v_mul_f32_dpp v202, -v110, v172 row_shl:4 row_mask:0xf bank_mask:0x5
	v_mul_f32_dpp v202, v110, v172 row_shr:4 row_mask:0xf bank_mask:0xa
	v_mul_f32_dpp v203, -v78, v173 row_shl:4 row_mask:0xf bank_mask:0x5
	v_mul_f32_dpp v203, v78, v173 row_shr:4 row_mask:0xf bank_mask:0xa
	v_fma_f32 v126, v126, v238, v200
	v_fma_f32 v94, v94, v239, v201
	v_fma_f32 v110, v110, v240, v202
	v_fma_f32 v78, v78, v241, v203
	v_cvt_pk_bf16_f32 v180, v126, v94
	v_cvt_pk_bf16_f32 v181, v110, v78
	global_store_dwordx2 v206, v[180:181], s[10:11]
	s_add_u32 s10, s10, 0x1400
	s_addc_u32 s11, s11, 0
	ds_read_b128 v[238:241], v178 offset:57344
	ds_read_b128 v[170:173], v178 offset:61440
	v_add_u32_e32 v178, v178, v207
	s_waitcnt lgkmcnt(4)
	v_mul_f32_dpp v200, -v127, v190 row_shl:4 row_mask:0xf bank_mask:0x5
	v_mul_f32_dpp v200, v127, v190 row_shr:4 row_mask:0xf bank_mask:0xa
	v_mul_f32_dpp v201, -v95, v191 row_shl:4 row_mask:0xf bank_mask:0x5
	v_mul_f32_dpp v201, v95, v191 row_shr:4 row_mask:0xf bank_mask:0xa
	v_mul_f32_dpp v202, -v111, v192 row_shl:4 row_mask:0xf bank_mask:0x5
	v_mul_f32_dpp v202, v111, v192 row_shr:4 row_mask:0xf bank_mask:0xa
	v_mul_f32_dpp v203, -v79, v193 row_shl:4 row_mask:0xf bank_mask:0x5
	v_mul_f32_dpp v203, v79, v193 row_shr:4 row_mask:0xf bank_mask:0xa
	v_fma_f32 v127, v127, v174, v200
	v_fma_f32 v95, v95, v175, v201
	v_fma_f32 v111, v111, v176, v202
	v_fma_f32 v79, v79, v177, v203
	v_cvt_pk_bf16_f32 v204, v127, v95
	v_cvt_pk_bf16_f32 v205, v111, v79
	global_store_dwordx2 v206, v[204:205], s[10:11]
	s_add_u32 s10, s10, 0x1400
	s_addc_u32 s11, s11, 0
	ds_read_b128 v[174:177], v178 offset:57344
	ds_read_b128 v[190:193], v178 offset:61440
	v_add_u32_e32 v178, v178, v179
	s_waitcnt lgkmcnt(4)
	v_mul_f32_dpp v200, -v128, v252 row_shl:4 row_mask:0xf bank_mask:0x5
	v_mul_f32_dpp v200, v128, v252 row_shr:4 row_mask:0xf bank_mask:0xa
	v_mul_f32_dpp v201, -v96, v253 row_shl:4 row_mask:0xf bank_mask:0x5
	v_mul_f32_dpp v201, v96, v253 row_shr:4 row_mask:0xf bank_mask:0xa
	v_mul_f32_dpp v202, -v112, v254 row_shl:4 row_mask:0xf bank_mask:0x5
	v_mul_f32_dpp v202, v112, v254 row_shr:4 row_mask:0xf bank_mask:0xa
	v_mul_f32_dpp v203, -v80, v255 row_shl:4 row_mask:0xf bank_mask:0x5
	v_mul_f32_dpp v203, v80, v255 row_shr:4 row_mask:0xf bank_mask:0xa
	v_fma_f32 v128, v128, v248, v200
	v_fma_f32 v96, v96, v249, v201
	v_fma_f32 v112, v112, v250, v202
	v_fma_f32 v80, v80, v251, v203
	v_cvt_pk_bf16_f32 v180, v128, v96
	v_cvt_pk_bf16_f32 v181, v112, v80
	global_store_dwordx2 v206, v[180:181], s[10:11]
	s_add_u32 s10, s10, 0x1400
	s_addc_u32 s11, s11, 0
	ds_read_b128 v[248:251], v178 offset:57344
	ds_read_b128 v[252:255], v178 offset:61440
	v_add_u32_e32 v178, v178, v179
	s_waitcnt lgkmcnt(4)
	v_mul_f32_dpp v200, -v129, v170 row_shl:4 row_mask:0xf bank_mask:0x5
	v_mul_f32_dpp v200, v129, v170 row_shr:4 row_mask:0xf bank_mask:0xa
	v_mul_f32_dpp v201, -v97, v171 row_shl:4 row_mask:0xf bank_mask:0x5
	v_mul_f32_dpp v201, v97, v171 row_shr:4 row_mask:0xf bank_mask:0xa
	v_mul_f32_dpp v202, -v113, v172 row_shl:4 row_mask:0xf bank_mask:0x5
	v_mul_f32_dpp v202, v113, v172 row_shr:4 row_mask:0xf bank_mask:0xa
	v_mul_f32_dpp v203, -v81, v173 row_shl:4 row_mask:0xf bank_mask:0x5
	v_mul_f32_dpp v203, v81, v173 row_shr:4 row_mask:0xf bank_mask:0xa
	v_fma_f32 v129, v129, v238, v200
	v_fma_f32 v97, v97, v239, v201
	v_fma_f32 v113, v113, v240, v202
	v_fma_f32 v81, v81, v241, v203
	v_cvt_pk_bf16_f32 v204, v129, v97
	v_cvt_pk_bf16_f32 v205, v113, v81
	global_store_dwordx2 v206, v[204:205], s[10:11]
	s_add_u32 s10, s10, 0x6400
	s_addc_u32 s11, s11, 0
	ds_read_b128 v[238:241], v178 offset:57344
	ds_read_b128 v[170:173], v178 offset:61440
	v_add_u32_e32 v178, v178, v179
	s_waitcnt lgkmcnt(4)
	v_mul_f32_dpp v200, -v50, v190 row_shl:4 row_mask:0xf bank_mask:0x5
	v_mul_f32_dpp v200, v50, v190 row_shr:4 row_mask:0xf bank_mask:0xa
	v_mul_f32_dpp v201, -v18, v191 row_shl:4 row_mask:0xf bank_mask:0x5
	v_mul_f32_dpp v201, v18, v191 row_shr:4 row_mask:0xf bank_mask:0xa
	v_mul_f32_dpp v202, -v34, v192 row_shl:4 row_mask:0xf bank_mask:0x5
	v_mul_f32_dpp v202, v34, v192 row_shr:4 row_mask:0xf bank_mask:0xa
	v_mul_f32_dpp v203, -v2, v193 row_shl:4 row_mask:0xf bank_mask:0x5
	v_mul_f32_dpp v203, v2, v193 row_shr:4 row_mask:0xf bank_mask:0xa
	v_fma_f32 v50, v50, v174, v200
	v_fma_f32 v18, v18, v175, v201
	v_fma_f32 v34, v34, v176, v202
	v_fma_f32 v2, v2, v177, v203
	v_cvt_pk_bf16_f32 v180, v50, v18
	v_cvt_pk_bf16_f32 v181, v34, v2
	global_store_dwordx2 v206, v[180:181], s[10:11]
	s_add_u32 s10, s10, 0x1400
	s_addc_u32 s11, s11, 0
	ds_read_b128 v[174:177], v178 offset:57344
	ds_read_b128 v[190:193], v178 offset:61440
	v_add_u32_e32 v178, v178, v207
	s_waitcnt lgkmcnt(4)
	v_mul_f32_dpp v200, -v51, v252 row_shl:4 row_mask:0xf bank_mask:0x5
	v_mul_f32_dpp v200, v51, v252 row_shr:4 row_mask:0xf bank_mask:0xa
	v_mul_f32_dpp v201, -v19, v253 row_shl:4 row_mask:0xf bank_mask:0x5
	v_mul_f32_dpp v201, v19, v253 row_shr:4 row_mask:0xf bank_mask:0xa
	v_mul_f32_dpp v202, -v35, v254 row_shl:4 row_mask:0xf bank_mask:0x5
	v_mul_f32_dpp v202, v35, v254 row_shr:4 row_mask:0xf bank_mask:0xa
	v_mul_f32_dpp v203, -v3, v255 row_shl:4 row_mask:0xf bank_mask:0x5
	v_mul_f32_dpp v203, v3, v255 row_shr:4 row_mask:0xf bank_mask:0xa
	v_fma_f32 v51, v51, v248, v200
	v_fma_f32 v19, v19, v249, v201
	v_fma_f32 v35, v35, v250, v202
	v_fma_f32 v3, v3, v251, v203
	v_cvt_pk_bf16_f32 v204, v51, v19
	v_cvt_pk_bf16_f32 v205, v35, v3
	global_store_dwordx2 v206, v[204:205], s[10:11]
	s_add_u32 s10, s10, 0x1400
	s_addc_u32 s11, s11, 0
	ds_read_b128 v[248:251], v178 offset:57344
	ds_read_b128 v[252:255], v178 offset:61440
	v_add_u32_e32 v178, v178, v179
	s_waitcnt lgkmcnt(4)
	v_mul_f32_dpp v200, -v52, v170 row_shl:4 row_mask:0xf bank_mask:0x5
	v_mul_f32_dpp v200, v52, v170 row_shr:4 row_mask:0xf bank_mask:0xa
	v_mul_f32_dpp v201, -v20, v171 row_shl:4 row_mask:0xf bank_mask:0x5
	v_mul_f32_dpp v201, v20, v171 row_shr:4 row_mask:0xf bank_mask:0xa
	v_mul_f32_dpp v202, -v36, v172 row_shl:4 row_mask:0xf bank_mask:0x5
	v_mul_f32_dpp v202, v36, v172 row_shr:4 row_mask:0xf bank_mask:0xa
	v_mul_f32_dpp v203, -v4, v173 row_shl:4 row_mask:0xf bank_mask:0x5
	v_mul_f32_dpp v203, v4, v173 row_shr:4 row_mask:0xf bank_mask:0xa
	v_fma_f32 v52, v52, v238, v200
	v_fma_f32 v20, v20, v239, v201
	v_fma_f32 v36, v36, v240, v202
	v_fma_f32 v4, v4, v241, v203
	v_cvt_pk_bf16_f32 v180, v52, v20
	v_cvt_pk_bf16_f32 v181, v36, v4
	global_store_dwordx2 v206, v[180:181], s[10:11]
	s_add_u32 s10, s10, 0x1400
	s_addc_u32 s11, s11, 0
	ds_read_b128 v[238:241], v178 offset:57344
	ds_read_b128 v[170:173], v178 offset:61440
	v_add_u32_e32 v178, v178, v179
	s_waitcnt lgkmcnt(4)
	v_mul_f32_dpp v200, -v53, v190 row_shl:4 row_mask:0xf bank_mask:0x5
	v_mul_f32_dpp v200, v53, v190 row_shr:4 row_mask:0xf bank_mask:0xa
	v_mul_f32_dpp v201, -v21, v191 row_shl:4 row_mask:0xf bank_mask:0x5
	v_mul_f32_dpp v201, v21, v191 row_shr:4 row_mask:0xf bank_mask:0xa
	v_mul_f32_dpp v202, -v37, v192 row_shl:4 row_mask:0xf bank_mask:0x5
	v_mul_f32_dpp v202, v37, v192 row_shr:4 row_mask:0xf bank_mask:0xa
	v_mul_f32_dpp v203, -v5, v193 row_shl:4 row_mask:0xf bank_mask:0x5
	v_mul_f32_dpp v203, v5, v193 row_shr:4 row_mask:0xf bank_mask:0xa
	v_fma_f32 v53, v53, v174, v200
	v_fma_f32 v21, v21, v175, v201
	v_fma_f32 v37, v37, v176, v202
	v_fma_f32 v5, v5, v177, v203
	v_cvt_pk_bf16_f32 v204, v53, v21
	v_cvt_pk_bf16_f32 v205, v37, v5
	global_store_dwordx2 v206, v[204:205], s[10:11]
	s_add_u32 s10, s10, 0x6400
	s_addc_u32 s11, s11, 0
	ds_read_b128 v[174:177], v178 offset:57344
	ds_read_b128 v[190:193], v178 offset:61440
	v_add_u32_e32 v178, v178, v179
	s_waitcnt lgkmcnt(4)
	v_mul_f32_dpp v200, -v54, v252 row_shl:4 row_mask:0xf bank_mask:0x5
	v_mul_f32_dpp v200, v54, v252 row_shr:4 row_mask:0xf bank_mask:0xa
	v_mul_f32_dpp v201, -v22, v253 row_shl:4 row_mask:0xf bank_mask:0x5
	v_mul_f32_dpp v201, v22, v253 row_shr:4 row_mask:0xf bank_mask:0xa
	v_mul_f32_dpp v202, -v38, v254 row_shl:4 row_mask:0xf bank_mask:0x5
	v_mul_f32_dpp v202, v38, v254 row_shr:4 row_mask:0xf bank_mask:0xa
	v_mul_f32_dpp v203, -v6, v255 row_shl:4 row_mask:0xf bank_mask:0x5
	v_mul_f32_dpp v203, v6, v255 row_shr:4 row_mask:0xf bank_mask:0xa
	v_fma_f32 v54, v54, v248, v200
	v_fma_f32 v22, v22, v249, v201
	v_fma_f32 v38, v38, v250, v202
	v_fma_f32 v6, v6, v251, v203
	v_cvt_pk_bf16_f32 v180, v54, v22
	v_cvt_pk_bf16_f32 v181, v38, v6
	global_store_dwordx2 v206, v[180:181], s[10:11]
	s_add_u32 s10, s10, 0x1400
	s_addc_u32 s11, s11, 0
	ds_read_b128 v[248:251], v178 offset:57344
	ds_read_b128 v[252:255], v178 offset:61440
	v_add_u32_e32 v178, v178, v207
	s_waitcnt lgkmcnt(4)
	v_mul_f32_dpp v200, -v55, v170 row_shl:4 row_mask:0xf bank_mask:0x5
	v_mul_f32_dpp v200, v55, v170 row_shr:4 row_mask:0xf bank_mask:0xa
	v_mul_f32_dpp v201, -v23, v171 row_shl:4 row_mask:0xf bank_mask:0x5
	v_mul_f32_dpp v201, v23, v171 row_shr:4 row_mask:0xf bank_mask:0xa
	v_mul_f32_dpp v202, -v39, v172 row_shl:4 row_mask:0xf bank_mask:0x5
	v_mul_f32_dpp v202, v39, v172 row_shr:4 row_mask:0xf bank_mask:0xa
	v_mul_f32_dpp v203, -v7, v173 row_shl:4 row_mask:0xf bank_mask:0x5
	v_mul_f32_dpp v203, v7, v173 row_shr:4 row_mask:0xf bank_mask:0xa
	v_fma_f32 v55, v55, v238, v200
	v_fma_f32 v23, v23, v239, v201
	v_fma_f32 v39, v39, v240, v202
	v_fma_f32 v7, v7, v241, v203
	v_cvt_pk_bf16_f32 v204, v55, v23
	v_cvt_pk_bf16_f32 v205, v39, v7
	global_store_dwordx2 v206, v[204:205], s[10:11]
	s_add_u32 s10, s10, 0x1400
	s_addc_u32 s11, s11, 0
	ds_read_b128 v[238:241], v178 offset:57344
	ds_read_b128 v[170:173], v178 offset:61440
	v_add_u32_e32 v178, v178, v179
	s_waitcnt lgkmcnt(4)
	v_mul_f32_dpp v200, -v56, v190 row_shl:4 row_mask:0xf bank_mask:0x5
	v_mul_f32_dpp v200, v56, v190 row_shr:4 row_mask:0xf bank_mask:0xa
	v_mul_f32_dpp v201, -v24, v191 row_shl:4 row_mask:0xf bank_mask:0x5
	v_mul_f32_dpp v201, v24, v191 row_shr:4 row_mask:0xf bank_mask:0xa
	v_mul_f32_dpp v202, -v40, v192 row_shl:4 row_mask:0xf bank_mask:0x5
	v_mul_f32_dpp v202, v40, v192 row_shr:4 row_mask:0xf bank_mask:0xa
	v_mul_f32_dpp v203, -v8, v193 row_shl:4 row_mask:0xf bank_mask:0x5
	v_mul_f32_dpp v203, v8, v193 row_shr:4 row_mask:0xf bank_mask:0xa
	v_fma_f32 v56, v56, v174, v200
	v_fma_f32 v24, v24, v175, v201
	v_fma_f32 v40, v40, v176, v202
	v_fma_f32 v8, v8, v177, v203
	v_cvt_pk_bf16_f32 v180, v56, v24
	v_cvt_pk_bf16_f32 v181, v40, v8
	global_store_dwordx2 v206, v[180:181], s[10:11]
	s_add_u32 s10, s10, 0x1400
	s_addc_u32 s11, s11, 0
	ds_read_b128 v[174:177], v178 offset:57344
	ds_read_b128 v[190:193], v178 offset:61440
	v_add_u32_e32 v178, v178, v179
	s_waitcnt lgkmcnt(4)
	v_mul_f32_dpp v200, -v57, v252 row_shl:4 row_mask:0xf bank_mask:0x5
	v_mul_f32_dpp v200, v57, v252 row_shr:4 row_mask:0xf bank_mask:0xa
	v_mul_f32_dpp v201, -v25, v253 row_shl:4 row_mask:0xf bank_mask:0x5
	v_mul_f32_dpp v201, v25, v253 row_shr:4 row_mask:0xf bank_mask:0xa
	v_mul_f32_dpp v202, -v41, v254 row_shl:4 row_mask:0xf bank_mask:0x5
	v_mul_f32_dpp v202, v41, v254 row_shr:4 row_mask:0xf bank_mask:0xa
	v_mul_f32_dpp v203, -v9, v255 row_shl:4 row_mask:0xf bank_mask:0x5
	v_mul_f32_dpp v203, v9, v255 row_shr:4 row_mask:0xf bank_mask:0xa
	v_fma_f32 v57, v57, v248, v200
	v_fma_f32 v25, v25, v249, v201
	v_fma_f32 v41, v41, v250, v202
	v_fma_f32 v9, v9, v251, v203
	v_cvt_pk_bf16_f32 v204, v57, v25
	v_cvt_pk_bf16_f32 v205, v41, v9
	global_store_dwordx2 v206, v[204:205], s[10:11]
	s_add_u32 s10, s10, 0x6400
	s_addc_u32 s11, s11, 0
	ds_read_b128 v[248:251], v178 offset:57344
	ds_read_b128 v[252:255], v178 offset:61440
	v_add_u32_e32 v178, v178, v179
	s_waitcnt lgkmcnt(4)
	v_mul_f32_dpp v200, -v58, v170 row_shl:4 row_mask:0xf bank_mask:0x5
	v_mul_f32_dpp v200, v58, v170 row_shr:4 row_mask:0xf bank_mask:0xa
	v_mul_f32_dpp v201, -v26, v171 row_shl:4 row_mask:0xf bank_mask:0x5
	v_mul_f32_dpp v201, v26, v171 row_shr:4 row_mask:0xf bank_mask:0xa
	v_mul_f32_dpp v202, -v42, v172 row_shl:4 row_mask:0xf bank_mask:0x5
	v_mul_f32_dpp v202, v42, v172 row_shr:4 row_mask:0xf bank_mask:0xa
	v_mul_f32_dpp v203, -v10, v173 row_shl:4 row_mask:0xf bank_mask:0x5
	v_mul_f32_dpp v203, v10, v173 row_shr:4 row_mask:0xf bank_mask:0xa
	v_fma_f32 v58, v58, v238, v200
	v_fma_f32 v26, v26, v239, v201
	v_fma_f32 v42, v42, v240, v202
	v_fma_f32 v10, v10, v241, v203
	v_cvt_pk_bf16_f32 v180, v58, v26
	v_cvt_pk_bf16_f32 v181, v42, v10
	global_store_dwordx2 v206, v[180:181], s[10:11]
	s_add_u32 s10, s10, 0x1400
	s_addc_u32 s11, s11, 0
	ds_read_b128 v[238:241], v178 offset:57344
	ds_read_b128 v[170:173], v178 offset:61440
	v_add_u32_e32 v178, v178, v207
	s_waitcnt lgkmcnt(4)
	v_mul_f32_dpp v200, -v59, v190 row_shl:4 row_mask:0xf bank_mask:0x5
	v_mul_f32_dpp v200, v59, v190 row_shr:4 row_mask:0xf bank_mask:0xa
	v_mul_f32_dpp v201, -v27, v191 row_shl:4 row_mask:0xf bank_mask:0x5
	v_mul_f32_dpp v201, v27, v191 row_shr:4 row_mask:0xf bank_mask:0xa
	v_mul_f32_dpp v202, -v43, v192 row_shl:4 row_mask:0xf bank_mask:0x5
	v_mul_f32_dpp v202, v43, v192 row_shr:4 row_mask:0xf bank_mask:0xa
	v_mul_f32_dpp v203, -v11, v193 row_shl:4 row_mask:0xf bank_mask:0x5
	v_mul_f32_dpp v203, v11, v193 row_shr:4 row_mask:0xf bank_mask:0xa
	v_fma_f32 v59, v59, v174, v200
	v_fma_f32 v27, v27, v175, v201
	v_fma_f32 v43, v43, v176, v202
	v_fma_f32 v11, v11, v177, v203
	v_cvt_pk_bf16_f32 v204, v59, v27
	v_cvt_pk_bf16_f32 v205, v43, v11
	global_store_dwordx2 v206, v[204:205], s[10:11]
	s_add_u32 s10, s10, 0x1400
	s_addc_u32 s11, s11, 0
	ds_read_b128 v[174:177], v178 offset:57344
	ds_read_b128 v[190:193], v178 offset:61440
	v_add_u32_e32 v178, v178, v179
	s_waitcnt lgkmcnt(4)
	v_mul_f32_dpp v200, -v60, v252 row_shl:4 row_mask:0xf bank_mask:0x5
	v_mul_f32_dpp v200, v60, v252 row_shr:4 row_mask:0xf bank_mask:0xa
	v_mul_f32_dpp v201, -v28, v253 row_shl:4 row_mask:0xf bank_mask:0x5
	v_mul_f32_dpp v201, v28, v253 row_shr:4 row_mask:0xf bank_mask:0xa
	v_mul_f32_dpp v202, -v44, v254 row_shl:4 row_mask:0xf bank_mask:0x5
	v_mul_f32_dpp v202, v44, v254 row_shr:4 row_mask:0xf bank_mask:0xa
	v_mul_f32_dpp v203, -v12, v255 row_shl:4 row_mask:0xf bank_mask:0x5
	v_mul_f32_dpp v203, v12, v255 row_shr:4 row_mask:0xf bank_mask:0xa
	v_fma_f32 v60, v60, v248, v200
	v_fma_f32 v28, v28, v249, v201
	v_fma_f32 v44, v44, v250, v202
	v_fma_f32 v12, v12, v251, v203
	v_cvt_pk_bf16_f32 v180, v60, v28
	v_cvt_pk_bf16_f32 v181, v44, v12
	global_store_dwordx2 v206, v[180:181], s[10:11]
	s_add_u32 s10, s10, 0x1400
	s_addc_u32 s11, s11, 0
	ds_read_b128 v[248:251], v178 offset:57344
	ds_read_b128 v[252:255], v178 offset:61440
	v_add_u32_e32 v178, v178, v179
	s_waitcnt lgkmcnt(4)
	v_mul_f32_dpp v200, -v61, v170 row_shl:4 row_mask:0xf bank_mask:0x5
	v_mul_f32_dpp v200, v61, v170 row_shr:4 row_mask:0xf bank_mask:0xa
	v_mul_f32_dpp v201, -v29, v171 row_shl:4 row_mask:0xf bank_mask:0x5
	v_mul_f32_dpp v201, v29, v171 row_shr:4 row_mask:0xf bank_mask:0xa
	v_mul_f32_dpp v202, -v45, v172 row_shl:4 row_mask:0xf bank_mask:0x5
	v_mul_f32_dpp v202, v45, v172 row_shr:4 row_mask:0xf bank_mask:0xa
	v_mul_f32_dpp v203, -v13, v173 row_shl:4 row_mask:0xf bank_mask:0x5
	v_mul_f32_dpp v203, v13, v173 row_shr:4 row_mask:0xf bank_mask:0xa
	v_fma_f32 v61, v61, v238, v200
	v_fma_f32 v29, v29, v239, v201
	v_fma_f32 v45, v45, v240, v202
	v_fma_f32 v13, v13, v241, v203
	v_cvt_pk_bf16_f32 v204, v61, v29
	v_cvt_pk_bf16_f32 v205, v45, v13
	global_store_dwordx2 v206, v[204:205], s[10:11]
	s_add_u32 s10, s10, 0x6400
	s_addc_u32 s11, s11, 0
	ds_read_b128 v[238:241], v178 offset:57344
	ds_read_b128 v[170:173], v178 offset:61440
	v_add_u32_e32 v178, v178, v179
	s_waitcnt lgkmcnt(4)
	v_mul_f32_dpp v200, -v62, v190 row_shl:4 row_mask:0xf bank_mask:0x5
	v_mul_f32_dpp v200, v62, v190 row_shr:4 row_mask:0xf bank_mask:0xa
	v_mul_f32_dpp v201, -v30, v191 row_shl:4 row_mask:0xf bank_mask:0x5
	v_mul_f32_dpp v201, v30, v191 row_shr:4 row_mask:0xf bank_mask:0xa
	v_mul_f32_dpp v202, -v46, v192 row_shl:4 row_mask:0xf bank_mask:0x5
	v_mul_f32_dpp v202, v46, v192 row_shr:4 row_mask:0xf bank_mask:0xa
	v_mul_f32_dpp v203, -v14, v193 row_shl:4 row_mask:0xf bank_mask:0x5
	v_mul_f32_dpp v203, v14, v193 row_shr:4 row_mask:0xf bank_mask:0xa
	v_fma_f32 v62, v62, v174, v200
	v_fma_f32 v30, v30, v175, v201
	v_fma_f32 v46, v46, v176, v202
	v_fma_f32 v14, v14, v177, v203
	v_cvt_pk_bf16_f32 v180, v62, v30
	v_cvt_pk_bf16_f32 v181, v46, v14
	global_store_dwordx2 v206, v[180:181], s[10:11]
	s_add_u32 s10, s10, 0x1400
	s_addc_u32 s11, s11, 0
	ds_read_b128 v[174:177], v178 offset:57344
	ds_read_b128 v[190:193], v178 offset:61440
	s_waitcnt lgkmcnt(4)
	v_mul_f32_dpp v200, -v63, v252 row_shl:4 row_mask:0xf bank_mask:0x5
	v_mul_f32_dpp v200, v63, v252 row_shr:4 row_mask:0xf bank_mask:0xa
	v_mul_f32_dpp v201, -v31, v253 row_shl:4 row_mask:0xf bank_mask:0x5
	v_mul_f32_dpp v201, v31, v253 row_shr:4 row_mask:0xf bank_mask:0xa
	v_mul_f32_dpp v202, -v47, v254 row_shl:4 row_mask:0xf bank_mask:0x5
	v_mul_f32_dpp v202, v47, v254 row_shr:4 row_mask:0xf bank_mask:0xa
	v_mul_f32_dpp v203, -v15, v255 row_shl:4 row_mask:0xf bank_mask:0x5
	v_mul_f32_dpp v203, v15, v255 row_shr:4 row_mask:0xf bank_mask:0xa
	v_fma_f32 v63, v63, v248, v200
	v_fma_f32 v31, v31, v249, v201
	v_fma_f32 v47, v47, v250, v202
	v_fma_f32 v15, v15, v251, v203
	v_cvt_pk_bf16_f32 v204, v63, v31
	v_cvt_pk_bf16_f32 v205, v47, v15
	global_store_dwordx2 v206, v[204:205], s[10:11]
	s_add_u32 s10, s10, 0x1400
	s_addc_u32 s11, s11, 0
	s_waitcnt lgkmcnt(2)
	v_mul_f32_dpp v200, -v64, v170 row_shl:4 row_mask:0xf bank_mask:0x5
	v_mul_f32_dpp v200, v64, v170 row_shr:4 row_mask:0xf bank_mask:0xa
	v_mul_f32_dpp v201, -v32, v171 row_shl:4 row_mask:0xf bank_mask:0x5
	v_mul_f32_dpp v201, v32, v171 row_shr:4 row_mask:0xf bank_mask:0xa
	v_mul_f32_dpp v202, -v48, v172 row_shl:4 row_mask:0xf bank_mask:0x5
	v_mul_f32_dpp v202, v48, v172 row_shr:4 row_mask:0xf bank_mask:0xa
	v_mul_f32_dpp v203, -v16, v173 row_shl:4 row_mask:0xf bank_mask:0x5
	v_mul_f32_dpp v203, v16, v173 row_shr:4 row_mask:0xf bank_mask:0xa
	v_fma_f32 v64, v64, v238, v200
	v_fma_f32 v32, v32, v239, v201
	v_fma_f32 v48, v48, v240, v202
	v_fma_f32 v16, v16, v241, v203
	v_cvt_pk_bf16_f32 v180, v64, v32
	v_cvt_pk_bf16_f32 v181, v48, v16
	global_store_dwordx2 v206, v[180:181], s[10:11]
	s_add_u32 s10, s10, 0x1400
	s_addc_u32 s11, s11, 0
	s_waitcnt lgkmcnt(0)
	v_mul_f32_dpp v200, -v65, v190 row_shl:4 row_mask:0xf bank_mask:0x5
	v_mul_f32_dpp v200, v65, v190 row_shr:4 row_mask:0xf bank_mask:0xa
	v_mul_f32_dpp v201, -v33, v191 row_shl:4 row_mask:0xf bank_mask:0x5
	v_mul_f32_dpp v201, v33, v191 row_shr:4 row_mask:0xf bank_mask:0xa
	v_mul_f32_dpp v202, -v49, v192 row_shl:4 row_mask:0xf bank_mask:0x5
	v_mul_f32_dpp v202, v49, v192 row_shr:4 row_mask:0xf bank_mask:0xa
	v_mul_f32_dpp v203, -v17, v193 row_shl:4 row_mask:0xf bank_mask:0x5
	v_mul_f32_dpp v203, v17, v193 row_shr:4 row_mask:0xf bank_mask:0xa
	v_fma_f32 v65, v65, v174, v200
	v_fma_f32 v33, v33, v175, v201
	v_fma_f32 v49, v49, v176, v202
	v_fma_f32 v17, v17, v177, v203
	v_cvt_pk_bf16_f32 v204, v65, v33
	v_cvt_pk_bf16_f32 v205, v49, v17
	global_store_dwordx2 v206, v[204:205], s[10:11]
	s_branch .LBB0_181
